# stack4 + attention PV segments: 12 transition lgkmcnt(0) waits swapped with the following MFMA whose operands the previous wait already drained (pure reorder)
# speedup vs baseline: 1.0031x; 1.0031x over previous
.LBB0_518:
	ds_read_b128 v[66:69], v213 offset:49152
	ds_read_b128 v[70:73], v213 offset:57344
	ds_read_b128 v[226:229], v214 offset:49152
	ds_read_b128 v[230:233], v214 offset:57344
	v_add_f32_e32 v162, 0, v177
	v_add_f32_e32 v162, v191, v162
	s_waitcnt lgkmcnt(3)
	v_mfma_f32_32x32x16_bf16 v[82:97], v[66:69], v[126:129], 0
	v_add_f32_e32 v162, v163, v162
	v_add_f32_e32 v162, v190, v162
	v_add_f32_e32 v162, v164, v162
	v_add_f32_e32 v162, v176, v162
	v_add_f32_e32 v162, v165, v162
	v_add_f32_e32 v162, v175, v162
	v_add_f32_e32 v162, v166, v162
	s_waitcnt lgkmcnt(2)
	v_mfma_f32_32x32x16_bf16 v[66:81], v[70:73], v[126:129], 0
	v_add_f32_e32 v162, v173, v162
	v_add_f32_e32 v162, v167, v162
	v_add_f32_e32 v162, v172, v162
	v_exp_f32_e32 v158, v158
	v_add_f32_e32 v162, v168, v162
	v_exp_f32_e32 v159, v159
	v_add_f32_e32 v162, v170, v162
	s_waitcnt lgkmcnt(1)
	v_mfma_f32_32x32x16_bf16 v[82:97], v[226:229], v[122:125], v[82:97]
	v_exp_f32_e32 v156, v156
	v_add_f32_e32 v162, v169, v162
	v_exp_f32_e32 v157, v157
	v_add_f32_e32 v162, v171, v162
	v_exp_f32_e32 v152, v152
	v_add_f32_e32 v162, v158, v162
	v_exp_f32_e32 v153, v153
	s_waitcnt lgkmcnt(0)
	v_mfma_f32_32x32x16_bf16 v[66:81], v[230:233], v[122:125], v[66:81]
	ds_read_b128 v[226:229], v215 offset:49152
	ds_read_b128 v[230:233], v215 offset:57344
	v_add_f32_e32 v162, v159, v162
	v_exp_f32_e32 v150, v150
	v_add_f32_e32 v162, v156, v162
	v_exp_f32_e32 v151, v151
	v_add_f32_e32 v162, v157, v162
	v_exp_f32_e32 v146, v146
	s_waitcnt lgkmcnt(1)
	v_mfma_f32_32x32x16_bf16 v[82:97], v[226:229], v[118:121], v[82:97]
	v_add_f32_e32 v162, v152, v162
	v_exp_f32_e32 v147, v147
	v_add_f32_e32 v162, v153, v162
	v_exp_f32_e32 v160, v160
	v_add_f32_e32 v162, v150, v162
	v_exp_f32_e32 v161, v161
	v_add_f32_e32 v162, v151, v162
	s_waitcnt lgkmcnt(0)
	v_mfma_f32_32x32x16_bf16 v[66:81], v[230:233], v[118:121], v[66:81]
	ds_read_b128 v[226:229], v216 offset:49152
	ds_read_b128 v[230:233], v216 offset:57344
	v_exp_f32_e32 v154, v154
	v_add_f32_e32 v162, v146, v162
	v_exp_f32_e32 v155, v155
	v_add_f32_e32 v162, v147, v162
	v_exp_f32_e32 v148, v148
	v_add_f32_e32 v162, v160, v162
	s_waitcnt lgkmcnt(1)
	v_mfma_f32_32x32x16_bf16 v[82:97], v[226:229], v[114:117], v[82:97]
	v_exp_f32_e32 v149, v149
	v_add_f32_e32 v162, v161, v162
	v_add_f32_e32 v162, v154, v162
	v_add_f32_e32 v162, v155, v162
	v_add_f32_e32 v162, v148, v162
	v_add_f32_e32 v225, v149, v162
	s_waitcnt lgkmcnt(0)
	v_mfma_f32_32x32x16_bf16 v[66:81], v[230:233], v[114:117], v[66:81]
	ds_read_b128 v[226:229], v217 offset:49152
	ds_read_b128 v[230:233], v217 offset:57344
	s_waitcnt lgkmcnt(1)
	v_mfma_f32_32x32x16_bf16 v[82:97], v[226:229], v[110:113], v[82:97]
	s_waitcnt lgkmcnt(0)
	v_mfma_f32_32x32x16_bf16 v[66:81], v[230:233], v[110:113], v[66:81]
	ds_read_b128 v[226:229], v218 offset:49152
	ds_read_b128 v[230:233], v218 offset:57344
	s_waitcnt lgkmcnt(1)
	v_mfma_f32_32x32x16_bf16 v[82:97], v[226:229], v[106:109], v[82:97]
	s_waitcnt lgkmcnt(0)
	v_mfma_f32_32x32x16_bf16 v[66:81], v[230:233], v[106:109], v[66:81]
	ds_read_b128 v[226:229], v219 offset:49152
	ds_read_b128 v[230:233], v219 offset:57344
	s_waitcnt lgkmcnt(1)
	v_mfma_f32_32x32x16_bf16 v[82:97], v[226:229], v[102:105], v[82:97]
	s_waitcnt lgkmcnt(0)
	v_mfma_f32_32x32x16_bf16 v[66:81], v[230:233], v[102:105], v[66:81]
	ds_read_b128 v[226:229], v220 offset:49152
	ds_read_b128 v[230:233], v220 offset:57344
	v_cvt_pk_bf16_f32 v162, v177, v191
	v_cvt_pk_bf16_f32 v163, v163, v190
	v_cvt_pk_bf16_f32 v164, v164, v176
	v_cvt_pk_bf16_f32 v165, v165, v175
	v_cvt_pk_bf16_f32 v166, v166, v173
	v_cvt_pk_bf16_f32 v167, v167, v172
	s_waitcnt lgkmcnt(1)
	v_mfma_f32_32x32x16_bf16 v[82:97], v[226:229], v[98:101], v[82:97]
	v_mov_b32_e32 v226, v225
	s_nop 1
	v_permlane32_swap_b32_e32 v225, v226
	v_permlane32_swap_b32_e32 v162, v164
	v_cvt_pk_bf16_f32 v168, v168, v170
	v_cvt_pk_bf16_f32 v169, v169, v171
	s_waitcnt lgkmcnt(0)
	v_mfma_f32_32x32x16_bf16 v[66:81], v[230:233], v[98:101], v[66:81]
	v_cvt_pk_bf16_f32 v170, v158, v159
	v_cvt_pk_bf16_f32 v171, v156, v157
	v_cvt_pk_bf16_f32 v172, v152, v153
	v_cvt_pk_bf16_f32 v173, v150, v151
	v_cvt_pk_bf16_f32 v228, v146, v147
	v_cvt_pk_bf16_f32 v229, v160, v161
	v_cvt_pk_bf16_f32 v230, v154, v155
	v_cvt_pk_bf16_f32 v231, v148, v149
	v_permlane32_swap_b32_e32 v163, v165
	v_permlane32_swap_b32_e32 v166, v168
	v_permlane32_swap_b32_e32 v167, v169
	v_permlane32_swap_b32_e32 v170, v172
	v_permlane32_swap_b32_e32 v171, v173
	v_permlane32_swap_b32_e32 v228, v230
	v_permlane32_swap_b32_e32 v229, v231
	v_lshl_add_u64 v[192:193], v[186:187], 0, s[36:37]
	v_add_co_u32_e32 v146, vcc, s17, v192
	v_lshl_add_u64 v[190:191], v[188:189], 0, s[36:37]
	s_nop 0
	v_addc_co_u32_e32 v147, vcc, 0, v193, vcc
	v_add_co_u32_e32 v150, vcc, s20, v192
	s_nop 1
	v_addc_co_u32_e32 v151, vcc, 0, v193, vcc
	v_add_co_u32_e32 v154, vcc, s17, v190
	global_load_dwordx4 v[146:149], v[146:147], off
	s_nop 0
	global_load_dwordx4 v[150:153], v[150:151], off
	v_addc_co_u32_e32 v155, vcc, 0, v191, vcc
	v_add_co_u32_e32 v158, vcc, s20, v190
	s_nop 1
	v_addc_co_u32_e32 v159, vcc, 0, v191, vcc
	global_load_dwordx4 v[154:157], v[154:155], off
	s_nop 0
	global_load_dwordx4 v[158:161], v[158:159], off
	ds_read_b64_tr_b16 v[232:233], v194 offset:0
	ds_read_b64_tr_b16 v[234:235], v194 offset:0x800
	ds_read_b64_tr_b16 v[236:237], v194 offset:0x1000
	ds_read_b64_tr_b16 v[238:239], v194 offset:0x1800
	ds_read_b64_tr_b16 v[240:241], v194 offset:0x2000
	ds_read_b64_tr_b16 v[242:243], v194 offset:0x2800
	ds_read_b64_tr_b16 v[244:245], v194 offset:0x3000
	ds_read_b64_tr_b16 v[246:247], v194 offset:0x3800
	s_waitcnt lgkmcnt(0)
	s_nop 0
	v_mfma_f32_32x32x16_bf16 v[2:17], v[162:165], v[232:235], v[2:17]
	ds_read_b64_tr_b16 v[232:233], v194 offset:0x200
	ds_read_b64_tr_b16 v[234:235], v194 offset:0xa00
	v_mfma_f32_32x32x16_bf16 v[2:17], v[166:169], v[236:239], v[2:17]
	ds_read_b64_tr_b16 v[236:237], v194 offset:0x1200
	ds_read_b64_tr_b16 v[238:239], v194 offset:0x1a00
	v_mfma_f32_32x32x16_bf16 v[2:17], v[170:173], v[240:243], v[2:17]
	ds_read_b64_tr_b16 v[240:241], v194 offset:0x2200
	ds_read_b64_tr_b16 v[242:243], v194 offset:0x2a00
	ds_read_b64_tr_b16 v[248:249], v194 offset:0x3200
	ds_read_b64_tr_b16 v[250:251], v194 offset:0x3a00
	v_mfma_f32_32x32x16_bf16 v[2:17], v[228:231], v[244:247], v[2:17]
	s_waitcnt lgkmcnt(0)
	v_mfma_f32_32x32x16_bf16 v[50:65], v[162:165], v[232:235], v[50:65]
	ds_read_b64_tr_b16 v[232:233], v194 offset:0x400
	ds_read_b64_tr_b16 v[234:235], v194 offset:0xc00
	v_mfma_f32_32x32x16_bf16 v[50:65], v[166:169], v[236:239], v[50:65]
	ds_read_b64_tr_b16 v[236:237], v194 offset:0x1400
	ds_read_b64_tr_b16 v[238:239], v194 offset:0x1c00
	v_mfma_f32_32x32x16_bf16 v[50:65], v[170:173], v[240:243], v[50:65]
	ds_read_b64_tr_b16 v[240:241], v194 offset:0x2400
	ds_read_b64_tr_b16 v[242:243], v194 offset:0x2c00
	ds_read_b64_tr_b16 v[244:245], v194 offset:0x3400
	ds_read_b64_tr_b16 v[246:247], v194 offset:0x3c00
	v_mfma_f32_32x32x16_bf16 v[50:65], v[228:231], v[248:251], v[50:65]
	s_waitcnt lgkmcnt(0)
	v_mfma_f32_32x32x16_bf16 v[34:49], v[162:165], v[232:235], v[34:49]
	ds_read_b64_tr_b16 v[232:233], v194 offset:0x600
	ds_read_b64_tr_b16 v[234:235], v194 offset:0xe00
	v_mfma_f32_32x32x16_bf16 v[34:49], v[166:169], v[236:239], v[34:49]
	ds_read_b64_tr_b16 v[236:237], v194 offset:0x1600
	ds_read_b64_tr_b16 v[238:239], v194 offset:0x1e00
	v_mfma_f32_32x32x16_bf16 v[34:49], v[170:173], v[240:243], v[34:49]
	ds_read_b64_tr_b16 v[240:241], v194 offset:0x2600
	ds_read_b64_tr_b16 v[242:243], v194 offset:0x2e00
	ds_read_b64_tr_b16 v[248:249], v194 offset:0x3600
	ds_read_b64_tr_b16 v[250:251], v194 offset:0x3e00
	v_mfma_f32_32x32x16_bf16 v[34:49], v[228:231], v[244:247], v[34:49]
	s_waitcnt lgkmcnt(0)
	v_mfma_f32_32x32x16_bf16 v[18:33], v[162:165], v[232:235], v[18:33]
	v_max3_f32 v175, v82, v83, v84
	v_max3_f32 v176, v66, v67, v68
	v_max_f32_e32 v164, v81, v81
	v_max3_f32 v175, v175, v85, v86
	v_max3_f32 v176, v176, v69, v70
	v_max_f32_e32 v165, v97, v97
	v_max3_f32 v162, v176, v71, v72
	v_mfma_f32_32x32x16_bf16 v[18:33], v[166:169], v[236:239], v[18:33]
	v_max3_f32 v175, v175, v87, v88
	v_max3_f32 v162, v162, v73, v74
	v_max_f32_e32 v164, v165, v164
	v_max3_f32 v163, v175, v89, v90
	v_max3_f32 v162, v162, v75, v76
	s_nop 0
	v_max3_f32 v163, v163, v91, v92
	v_mfma_f32_32x32x16_bf16 v[18:33], v[170:173], v[240:243], v[18:33]
	v_max3_f32 v163, v163, v93, v94
	v_max3_f32 v162, v162, v77, v78
	s_barrier
	v_max3_f32 v163, v163, v95, v96
	v_max3_f32 v162, v162, v79, v80
	s_nop 0
	v_max3_f32 v162, v163, v162, v164
	v_max_f32_e32 v164, v174, v174
	v_mov_b32_e32 v163, v162
	s_nop 1
	v_permlane32_swap_b32_e32 v162, v163
	v_max_f32_e32 v163, v163, v163
	v_max_f32_e32 v162, v162, v162
	v_max_f32_e32 v162, v162, v163
	v_sub_f32_e32 v163, v162, v174
	v_max_f32_e32 v162, v164, v162
	v_mfma_f32_32x32x16_bf16 v[18:33], v[228:231], v[248:251], v[18:33]
	v_sub_f32_e32 v164, v174, v162
	v_mul_f32_e32 v164, 0x3e0293ee, v164
	v_exp_f32_e32 v164, v164
	v_cmp_ge_f32_e32 vcc, s16, v163
	s_cmp_eq_u64 vcc, exec
	s_cselect_b64 s[6:7], -1, 0
	s_waitcnt vmcnt(4)
	v_cndmask_b32_e64 v227, v164, 1.0, s[6:7]
	v_cmp_gt_f32_e32 vcc, 1.0, v227
	s_waitcnt vmcnt(4)
	ds_write_b128 v209, v[130:133]
	ds_write_b128 v210, v[134:137]
	ds_write_b128 v211, v[138:141] offset:32768
	ds_write_b128 v212, v[142:145] offset:32768
	s_cbranch_vccz .LBB0_522
	s_and_saveexec_b64 s[38:39], s[4:5]
	ds_write_b32 v222, v227 offset:128
	s_or_b64 exec, exec, s[38:39]
	s_waitcnt lgkmcnt(0)
	v_add_u32_e32 v163, s29, v195
	ds_read_b128 v[164:167], v163 offset:224
	ds_read_b128 v[168:171], v163 offset:192
	ds_read_b128 v[228:231], v163 offset:160
	ds_read_b128 v[232:235], v163 offset:128
	s_waitcnt lgkmcnt(3)
	v_pk_mul_f32 v[14:15], v[14:15], v[164:165]
	s_waitcnt lgkmcnt(2)
	v_pk_mul_f32 v[10:11], v[10:11], v[168:169]
	s_waitcnt lgkmcnt(1)
	v_pk_mul_f32 v[6:7], v[6:7], v[228:229]
	v_pk_mul_f32 v[16:17], v[16:17], v[166:167]
	v_pk_mul_f32 v[12:13], v[12:13], v[170:171]
	v_pk_mul_f32 v[8:9], v[8:9], v[230:231]
	s_waitcnt lgkmcnt(0)
	v_pk_mul_f32 v[4:5], v[4:5], v[234:235]
	v_pk_mul_f32 v[2:3], v[2:3], v[232:233]
	v_pk_mul_f32 v[62:63], v[62:63], v[164:165]
	v_pk_mul_f32 v[58:59], v[58:59], v[168:169]
	v_pk_mul_f32 v[54:55], v[54:55], v[228:229]
	v_pk_mul_f32 v[64:65], v[64:65], v[166:167]
	v_pk_mul_f32 v[60:61], v[60:61], v[170:171]
	v_pk_mul_f32 v[56:57], v[56:57], v[230:231]
	v_pk_mul_f32 v[52:53], v[52:53], v[234:235]
	v_pk_mul_f32 v[50:51], v[50:51], v[232:233]
	v_pk_mul_f32 v[46:47], v[46:47], v[164:165]
	v_pk_mul_f32 v[42:43], v[42:43], v[168:169]
	v_pk_mul_f32 v[38:39], v[38:39], v[228:229]
	v_pk_mul_f32 v[48:49], v[48:49], v[166:167]
	v_pk_mul_f32 v[44:45], v[44:45], v[170:171]
	v_pk_mul_f32 v[40:41], v[40:41], v[230:231]
	v_pk_mul_f32 v[36:37], v[36:37], v[234:235]
	v_pk_mul_f32 v[34:35], v[34:35], v[232:233]
	v_pk_mul_f32 v[30:31], v[30:31], v[164:165]
	v_pk_mul_f32 v[26:27], v[26:27], v[168:169]
	v_pk_mul_f32 v[22:23], v[22:23], v[228:229]
	v_pk_mul_f32 v[32:33], v[32:33], v[166:167]
	v_pk_mul_f32 v[28:29], v[28:29], v[170:171]
	v_pk_mul_f32 v[24:25], v[24:25], v[230:231]
	v_pk_mul_f32 v[20:21], v[20:21], v[234:235]
	v_pk_mul_f32 v[18:19], v[18:19], v[232:233]

.LBB0_524:
	ds_read_b64_tr_b16 v[190:191], v196 offset:0
	ds_read_b64_tr_b16 v[192:193], v196 offset:0x800
	ds_read_b64_tr_b16 v[232:233], v196 offset:0x1000
	ds_read_b64_tr_b16 v[234:235], v196 offset:0x1800
	ds_read_b64_tr_b16 v[236:237], v196 offset:0x2000
	ds_read_b64_tr_b16 v[238:239], v196 offset:0x2800
	ds_read_b64_tr_b16 v[240:241], v196 offset:0x3000
	ds_read_b64_tr_b16 v[242:243], v196 offset:0x3800
	s_waitcnt lgkmcnt(0)
	s_nop 0
	v_mfma_f32_32x32x16_bf16 v[2:17], v[166:169], v[190:193], v[2:17]
	ds_read_b64_tr_b16 v[190:191], v196 offset:0x200
	ds_read_b64_tr_b16 v[192:193], v196 offset:0xa00
	v_mfma_f32_32x32x16_bf16 v[2:17], v[162:165], v[232:235], v[2:17]
	ds_read_b64_tr_b16 v[232:233], v196 offset:0x1200
	ds_read_b64_tr_b16 v[234:235], v196 offset:0x1a00
	v_mfma_f32_32x32x16_bf16 v[2:17], v[170:173], v[236:239], v[2:17]
	ds_read_b64_tr_b16 v[236:237], v196 offset:0x2200
	ds_read_b64_tr_b16 v[238:239], v196 offset:0x2a00
	ds_read_b64_tr_b16 v[244:245], v196 offset:0x3200
	ds_read_b64_tr_b16 v[246:247], v196 offset:0x3a00
	v_mfma_f32_32x32x16_bf16 v[2:17], v[174:177], v[240:243], v[2:17]
	s_waitcnt lgkmcnt(0)
	v_mfma_f32_32x32x16_bf16 v[50:65], v[166:169], v[190:193], v[50:65]
	ds_read_b64_tr_b16 v[190:191], v196 offset:0x400
	ds_read_b64_tr_b16 v[192:193], v196 offset:0xc00
	v_mfma_f32_32x32x16_bf16 v[50:65], v[162:165], v[232:235], v[50:65]
	ds_read_b64_tr_b16 v[232:233], v196 offset:0x1400
	ds_read_b64_tr_b16 v[234:235], v196 offset:0x1c00
	v_mfma_f32_32x32x16_bf16 v[50:65], v[170:173], v[236:239], v[50:65]
	ds_read_b64_tr_b16 v[236:237], v196 offset:0x2400
	ds_read_b64_tr_b16 v[238:239], v196 offset:0x2c00
	ds_read_b64_tr_b16 v[240:241], v196 offset:0x3400
	ds_read_b64_tr_b16 v[242:243], v196 offset:0x3c00
	v_mfma_f32_32x32x16_bf16 v[50:65], v[174:177], v[244:247], v[50:65]
	s_waitcnt lgkmcnt(0)
	v_mfma_f32_32x32x16_bf16 v[34:49], v[166:169], v[190:193], v[34:49]
	ds_read_b64_tr_b16 v[190:191], v196 offset:0x600
	ds_read_b64_tr_b16 v[192:193], v196 offset:0xe00
	v_mfma_f32_32x32x16_bf16 v[34:49], v[162:165], v[232:235], v[34:49]
	ds_read_b64_tr_b16 v[232:233], v196 offset:0x1600
	ds_read_b64_tr_b16 v[234:235], v196 offset:0x1e00
	v_mfma_f32_32x32x16_bf16 v[34:49], v[170:173], v[236:239], v[34:49]
	ds_read_b64_tr_b16 v[236:237], v196 offset:0x2600
	ds_read_b64_tr_b16 v[238:239], v196 offset:0x2e00
	ds_read_b64_tr_b16 v[244:245], v196 offset:0x3600
	ds_read_b64_tr_b16 v[246:247], v196 offset:0x3e00
	v_mfma_f32_32x32x16_bf16 v[34:49], v[174:177], v[240:243], v[34:49]
	s_waitcnt lgkmcnt(0)
	v_mfma_f32_32x32x16_bf16 v[18:33], v[166:169], v[190:193], v[18:33]
	v_max3_f32 v231, v82, v83, v84
	v_max3_f32 v240, v66, v67, v68
	s_nop 0
	v_max3_f32 v231, v231, v85, v86
	v_max3_f32 v240, v240, v69, v70
	s_barrier
	v_max3_f32 v166, v240, v71, v72
	v_mfma_f32_32x32x16_bf16 v[18:33], v[162:165], v[232:235], v[18:33]
	v_max3_f32 v231, v231, v87, v88
	v_max3_f32 v166, v166, v73, v74
	v_max_f32_e32 v164, v81, v81
	v_max3_f32 v167, v231, v89, v90
	v_max3_f32 v166, v166, v75, v76
	v_max_f32_e32 v165, v97, v97
	v_max3_f32 v167, v167, v91, v92
	v_mfma_f32_32x32x16_bf16 v[18:33], v[170:173], v[236:239], v[18:33]
	v_max3_f32 v167, v167, v93, v94
	v_max3_f32 v166, v166, v77, v78
	v_max_f32_e32 v164, v165, v164
	v_max3_f32 v162, v167, v95, v96
	v_max3_f32 v163, v166, v79, v80
	s_nop 0
	v_max3_f32 v162, v162, v163, v164
	v_mfma_f32_32x32x16_bf16 v[18:33], v[174:177], v[244:247], v[18:33]
	v_mov_b32_e32 v163, v162
	s_nop 1
	v_permlane32_swap_b32_e32 v162, v163
	v_max_f32_e32 v163, v163, v163
	v_max_f32_e32 v162, v162, v162
	v_max_f32_e32 v162, v162, v163
	v_max_f32_e32 v163, v228, v228
	v_max_f32_e32 v163, v163, v162
	v_sub_f32_e32 v164, v162, v228
	v_sub_f32_e32 v162, v228, v163
	v_mul_f32_e32 v162, 0x3e0293ee, v162
	v_exp_f32_e32 v162, v162
	v_cmp_ge_f32_e32 vcc, s16, v164
	s_cmp_eq_u64 vcc, exec
	s_cselect_b64 s[6:7], -1, 0
	s_waitcnt vmcnt(4)
	v_cndmask_b32_e64 v162, v162, 1.0, s[6:7]
	v_cmp_gt_f32_e32 vcc, 1.0, v162
	s_cmp_eq_u64 s[38:39], 0
	s_cbranch_scc1 .Lattn_notlast
	s_waitcnt vmcnt(0)

.LBB0_530:
	ds_read_b128 v[66:69], v213 offset:49152
	ds_read_b128 v[70:73], v213 offset:57344
	v_exp_f32_e32 v158, v158
	v_exp_f32_e32 v159, v159
	v_exp_f32_e32 v156, v156
	s_waitcnt lgkmcnt(1)
	v_mfma_f32_32x32x16_bf16 v[82:97], v[66:69], v[126:129], 0
	v_exp_f32_e32 v157, v157
	v_exp_f32_e32 v152, v152
	s_waitcnt lgkmcnt(0)
	v_mfma_f32_32x32x16_bf16 v[66:81], v[70:73], v[126:129], 0
	ds_read_b128 v[126:129], v214 offset:49152
	ds_read_b128 v[130:133], v214 offset:57344
	ds_read_b128 v[134:137], v215 offset:49152
	ds_read_b128 v[138:141], v215 offset:57344
	s_waitcnt lgkmcnt(3)
	v_mfma_f32_32x32x16_bf16 v[82:97], v[126:129], v[122:125], v[82:97]
	ds_read_b128 v[126:129], v216 offset:49152
	ds_read_b128 v[142:145], v216 offset:57344
	ds_read_b128 v[186:189], v217 offset:49152
	ds_read_b128 v[224:227], v217 offset:57344
	ds_read_b128 v[228:231], v218 offset:49152
	ds_read_b128 v[232:235], v218 offset:57344
	ds_read_b128 v[236:239], v219 offset:49152
	ds_read_b128 v[240:243], v219 offset:57344
	s_waitcnt lgkmcnt(10)
	v_mfma_f32_32x32x16_bf16 v[66:81], v[130:133], v[122:125], v[66:81]
	ds_read_b128 v[122:125], v220 offset:49152
	ds_read_b128 v[130:133], v220 offset:57344
	s_waitcnt lgkmcnt(11)
	v_mfma_f32_32x32x16_bf16 v[82:97], v[134:137], v[118:121], v[82:97]
	v_exp_f32_e32 v134, v153
	v_exp_f32_e32 v135, v150
	v_exp_f32_e32 v136, v151
	v_exp_f32_e32 v137, v146
	v_exp_f32_e32 v146, v147
	v_exp_f32_e32 v147, v160
	v_exp_f32_e32 v150, v161
	s_waitcnt lgkmcnt(10)
	v_mfma_f32_32x32x16_bf16 v[66:81], v[138:141], v[118:121], v[66:81]
	v_add_f32_e32 v118, 0, v177
	v_add_f32_e32 v118, v191, v118
	v_add_f32_e32 v118, v163, v118
	v_add_f32_e32 v118, v190, v118
	v_add_f32_e32 v118, v164, v118
	v_add_f32_e32 v118, v176, v118
	v_add_f32_e32 v118, v165, v118
	s_waitcnt lgkmcnt(9)
	v_mfma_f32_32x32x16_bf16 v[82:97], v[126:129], v[114:117], v[82:97]
	v_add_f32_e32 v118, v175, v118
	v_add_f32_e32 v118, v166, v118
	v_add_f32_e32 v118, v173, v118
	v_exp_f32_e32 v120, v154
	v_exp_f32_e32 v121, v155
	v_exp_f32_e32 v138, v148
	v_exp_f32_e32 v139, v149
	s_waitcnt lgkmcnt(8)
	v_mfma_f32_32x32x16_bf16 v[66:81], v[142:145], v[114:117], v[66:81]
	v_add_f32_e32 v114, v167, v118
	v_add_f32_e32 v114, v172, v114
	v_add_f32_e32 v114, v168, v114
	v_add_f32_e32 v114, v170, v114
	v_add_f32_e32 v114, v169, v114
	v_add_f32_e32 v114, v171, v114
	v_add_f32_e32 v114, v158, v114
	s_waitcnt lgkmcnt(7)
	v_mfma_f32_32x32x16_bf16 v[82:97], v[186:189], v[110:113], v[82:97]
	v_add_f32_e32 v114, v159, v114
	v_add_f32_e32 v114, v156, v114
	v_add_f32_e32 v114, v157, v114
	v_add_f32_e32 v114, v152, v114
	v_add_f32_e32 v114, v134, v114
	v_add_f32_e32 v114, v135, v114
	v_add_f32_e32 v114, v136, v114
	s_waitcnt lgkmcnt(6)
	v_mfma_f32_32x32x16_bf16 v[66:81], v[224:227], v[110:113], v[66:81]
	v_add_f32_e32 v110, v137, v114
	v_add_f32_e32 v110, v146, v110
	v_add_f32_e32 v110, v147, v110
	v_add_f32_e32 v110, v150, v110
	v_add_f32_e32 v110, v120, v110
	v_add_f32_e32 v110, v121, v110
	v_add_f32_e32 v110, v138, v110
	s_waitcnt lgkmcnt(5)
	v_mfma_f32_32x32x16_bf16 v[82:97], v[228:231], v[106:109], v[82:97]
	v_add_f32_e32 v110, v139, v110
	v_mov_b32_e32 v111, v110
	s_nop 1
	v_permlane32_swap_b32_e32 v110, v111
	v_cvt_pk_bf16_f32 v112, v177, v191
	v_cvt_pk_bf16_f32 v113, v163, v190
	v_cvt_pk_bf16_f32 v114, v164, v176
	s_waitcnt lgkmcnt(4)
	v_mfma_f32_32x32x16_bf16 v[66:81], v[232:235], v[106:109], v[66:81]
	v_cvt_pk_bf16_f32 v115, v165, v175
	v_cvt_pk_bf16_f32 v106, v166, v173
	v_cvt_pk_bf16_f32 v107, v167, v172
	v_cvt_pk_bf16_f32 v108, v168, v170
	v_cvt_pk_bf16_f32 v109, v169, v171
	v_cvt_pk_bf16_f32 v116, v158, v159
	v_cvt_pk_bf16_f32 v117, v156, v157
	s_waitcnt lgkmcnt(3)
	v_mfma_f32_32x32x16_bf16 v[82:97], v[236:239], v[102:105], v[82:97]
	v_cvt_pk_bf16_f32 v118, v152, v134
	v_cvt_pk_bf16_f32 v119, v135, v136
	v_permlane32_swap_b32_e32 v112, v114
	v_permlane32_swap_b32_e32 v113, v115
	v_permlane32_swap_b32_e32 v106, v108
	s_waitcnt lgkmcnt(2)
	v_mfma_f32_32x32x16_bf16 v[66:81], v[240:243], v[102:105], v[66:81]
	v_cvt_pk_bf16_f32 v102, v137, v146
	v_cvt_pk_bf16_f32 v103, v147, v150
	v_cvt_pk_bf16_f32 v104, v120, v121
	v_cvt_pk_bf16_f32 v105, v138, v139
	v_permlane32_swap_b32_e32 v107, v109
	v_permlane32_swap_b32_e32 v116, v118
	s_waitcnt lgkmcnt(1)
	v_mfma_f32_32x32x16_bf16 v[82:97], v[122:125], v[98:101], v[82:97]
	v_permlane32_swap_b32_e32 v117, v119
	v_permlane32_swap_b32_e32 v102, v104
	v_permlane32_swap_b32_e32 v103, v105
	s_waitcnt lgkmcnt(0)
	v_mfma_f32_32x32x16_bf16 v[66:81], v[130:133], v[98:101], v[66:81]
	ds_read_b64_tr_b16 v[98:99], v194 offset:0
	ds_read_b64_tr_b16 v[100:101], v194 offset:0x800
	ds_read_b64_tr_b16 v[120:121], v194 offset:0x1000
	ds_read_b64_tr_b16 v[122:123], v194 offset:0x1800
	ds_read_b64_tr_b16 v[124:125], v194 offset:0x2000
	ds_read_b64_tr_b16 v[126:127], v194 offset:0x2800
	ds_read_b64_tr_b16 v[128:129], v194 offset:0x3000
	ds_read_b64_tr_b16 v[130:131], v194 offset:0x3800
	s_waitcnt lgkmcnt(0)
	s_nop 0
	v_mfma_f32_32x32x16_bf16 v[2:17], v[112:115], v[98:101], v[2:17]
	ds_read_b64_tr_b16 v[98:99], v194 offset:0x200
	ds_read_b64_tr_b16 v[100:101], v194 offset:0xa00
	v_mfma_f32_32x32x16_bf16 v[2:17], v[106:109], v[120:123], v[2:17]
	ds_read_b64_tr_b16 v[120:121], v194 offset:0x1200
	ds_read_b64_tr_b16 v[122:123], v194 offset:0x1a00
	v_mfma_f32_32x32x16_bf16 v[2:17], v[116:119], v[124:127], v[2:17]
	ds_read_b64_tr_b16 v[124:125], v194 offset:0x2200
	ds_read_b64_tr_b16 v[126:127], v194 offset:0x2a00
	ds_read_b64_tr_b16 v[132:133], v194 offset:0x3200
	ds_read_b64_tr_b16 v[134:135], v194 offset:0x3a00
	v_mfma_f32_32x32x16_bf16 v[2:17], v[102:105], v[128:131], v[2:17]
	s_waitcnt lgkmcnt(0)
	v_mfma_f32_32x32x16_bf16 v[50:65], v[112:115], v[98:101], v[50:65]
	ds_read_b64_tr_b16 v[98:99], v194 offset:0x400
	ds_read_b64_tr_b16 v[100:101], v194 offset:0xc00
	v_mfma_f32_32x32x16_bf16 v[50:65], v[106:109], v[120:123], v[50:65]
	ds_read_b64_tr_b16 v[120:121], v194 offset:0x1400
	ds_read_b64_tr_b16 v[122:123], v194 offset:0x1c00
	v_mfma_f32_32x32x16_bf16 v[50:65], v[116:119], v[124:127], v[50:65]
	ds_read_b64_tr_b16 v[124:125], v194 offset:0x2400
	ds_read_b64_tr_b16 v[126:127], v194 offset:0x2c00
	ds_read_b64_tr_b16 v[128:129], v194 offset:0x3400
	ds_read_b64_tr_b16 v[130:131], v194 offset:0x3c00
	v_mfma_f32_32x32x16_bf16 v[50:65], v[102:105], v[132:135], v[50:65]
	s_waitcnt lgkmcnt(0)
	v_mfma_f32_32x32x16_bf16 v[34:49], v[112:115], v[98:101], v[34:49]
	ds_read_b64_tr_b16 v[98:99], v194 offset:0x600
	ds_read_b64_tr_b16 v[100:101], v194 offset:0xe00
	v_mfma_f32_32x32x16_bf16 v[34:49], v[106:109], v[120:123], v[34:49]
	ds_read_b64_tr_b16 v[120:121], v194 offset:0x1600
	ds_read_b64_tr_b16 v[122:123], v194 offset:0x1e00
	v_mfma_f32_32x32x16_bf16 v[34:49], v[116:119], v[124:127], v[34:49]
	ds_read_b64_tr_b16 v[124:125], v194 offset:0x2600
	ds_read_b64_tr_b16 v[126:127], v194 offset:0x2e00
	ds_read_b64_tr_b16 v[132:133], v194 offset:0x3600
	ds_read_b64_tr_b16 v[134:135], v194 offset:0x3e00
	v_mfma_f32_32x32x16_bf16 v[34:49], v[102:105], v[128:131], v[34:49]
	s_waitcnt lgkmcnt(0)
	v_mfma_f32_32x32x16_bf16 v[18:33], v[112:115], v[98:101], v[18:33]
	v_max3_f32 v128, v82, v83, v84
	v_max3_f32 v129, v66, v67, v68
	v_max_f32_e32 v100, v81, v81
	v_max3_f32 v128, v128, v85, v86
	v_max3_f32 v129, v129, v69, v70
	v_max_f32_e32 v101, v97, v97
	v_max3_f32 v98, v129, v71, v72
	v_mfma_f32_32x32x16_bf16 v[18:33], v[106:109], v[120:123], v[18:33]
	v_max3_f32 v128, v128, v87, v88
	v_max3_f32 v98, v98, v73, v74
	v_max_f32_e32 v100, v101, v100
	v_max3_f32 v99, v128, v89, v90
	v_max3_f32 v98, v98, v75, v76
	s_nop 0
	v_max3_f32 v99, v99, v91, v92
	v_mfma_f32_32x32x16_bf16 v[18:33], v[116:119], v[124:127], v[18:33]
	v_max3_f32 v99, v99, v93, v94
	v_max3_f32 v98, v98, v77, v78
	s_barrier
	v_max3_f32 v99, v99, v95, v96
	v_max3_f32 v98, v98, v79, v80
	s_nop 0
	v_max3_f32 v98, v99, v98, v100
	v_mfma_f32_32x32x16_bf16 v[18:33], v[102:105], v[132:135], v[18:33]
	v_mov_b32_e32 v99, v98
	s_nop 1
	v_permlane32_swap_b32_e32 v98, v99
	v_max_f32_e32 v99, v99, v99
	v_max_f32_e32 v98, v98, v98
	v_max_f32_e32 v98, v98, v99
	v_max_f32_e32 v99, v174, v174
	v_max_f32_e32 v99, v99, v98
	v_sub_f32_e32 v100, v98, v174
	v_sub_f32_e32 v98, v174, v99
	v_mul_f32_e32 v98, 0x3e0293ee, v98
	v_exp_f32_e32 v98, v98
	v_cmp_ge_f32_e32 vcc, s16, v100
	s_cmp_eq_u64 vcc, exec
	s_cselect_b64 s[6:7], -1, 0
	v_cndmask_b32_e64 v98, v98, 1.0, s[6:7]
	v_cmp_gt_f32_e32 vcc, 1.0, v98
	s_cbranch_vccz .LBB0_534
	s_and_saveexec_b64 s[36:37], s[4:5]
	ds_write_b32 v222, v98 offset:128
	s_or_b64 exec, exec, s[36:37]
	s_waitcnt lgkmcnt(0)
	v_add_u32_e32 v108, s29, v195
	ds_read_b128 v[100:103], v108 offset:224
	ds_read_b128 v[104:107], v108 offset:192
	ds_read_b128 v[112:115], v108 offset:160
	ds_read_b128 v[116:119], v108 offset:128
	s_waitcnt lgkmcnt(3)
	v_pk_mul_f32 v[14:15], v[14:15], v[100:101]
	s_waitcnt lgkmcnt(2)
	v_pk_mul_f32 v[10:11], v[10:11], v[104:105]
	s_waitcnt lgkmcnt(1)
	v_pk_mul_f32 v[6:7], v[6:7], v[112:113]
	v_pk_mul_f32 v[16:17], v[16:17], v[102:103]
	v_pk_mul_f32 v[12:13], v[12:13], v[106:107]
	v_pk_mul_f32 v[8:9], v[8:9], v[114:115]
	s_waitcnt lgkmcnt(0)
	v_pk_mul_f32 v[4:5], v[4:5], v[118:119]
	v_pk_mul_f32 v[2:3], v[2:3], v[116:117]
	v_pk_mul_f32 v[62:63], v[62:63], v[100:101]
	v_pk_mul_f32 v[58:59], v[58:59], v[104:105]
	v_pk_mul_f32 v[54:55], v[54:55], v[112:113]
	v_pk_mul_f32 v[64:65], v[64:65], v[102:103]
	v_pk_mul_f32 v[60:61], v[60:61], v[106:107]
	v_pk_mul_f32 v[56:57], v[56:57], v[114:115]
	v_pk_mul_f32 v[52:53], v[52:53], v[118:119]
	v_pk_mul_f32 v[50:51], v[50:51], v[116:117]
	v_pk_mul_f32 v[46:47], v[46:47], v[100:101]
	v_pk_mul_f32 v[42:43], v[42:43], v[104:105]
	v_pk_mul_f32 v[38:39], v[38:39], v[112:113]
	v_pk_mul_f32 v[48:49], v[48:49], v[102:103]
	v_pk_mul_f32 v[44:45], v[44:45], v[106:107]
	v_pk_mul_f32 v[40:41], v[40:41], v[114:115]
	v_pk_mul_f32 v[36:37], v[36:37], v[118:119]
	v_pk_mul_f32 v[34:35], v[34:35], v[116:117]
	v_pk_mul_f32 v[30:31], v[30:31], v[100:101]
	v_pk_mul_f32 v[26:27], v[26:27], v[104:105]
	v_pk_mul_f32 v[22:23], v[22:23], v[112:113]
	v_pk_mul_f32 v[32:33], v[32:33], v[102:103]
	v_pk_mul_f32 v[28:29], v[28:29], v[106:107]
	v_pk_mul_f32 v[24:25], v[24:25], v[114:115]
	v_pk_mul_f32 v[20:21], v[20:21], v[118:119]
	v_pk_mul_f32 v[18:19], v[18:19], v[116:117]
.LBB0_534:
	v_cndmask_b32_e64 v99, v99, v174, s[6:7]
	v_mul_f32_e32 v99, 0xbe0293ee, v99
	v_fmamk_f32 v82, v82, 0x3e0293ee, v99
	v_fmamk_f32 v83, v83, 0x3e0293ee, v99
	v_fmamk_f32 v100, v84, 0x3e0293ee, v99
	v_exp_f32_e32 v84, v82
	v_fmamk_f32 v101, v86, 0x3e0293ee, v99
	v_exp_f32_e32 v86, v83
	v_fmamk_f32 v85, v85, 0x3e0293ee, v99
	v_exp_f32_e32 v82, v100
	v_fmamk_f32 v66, v66, 0x3e0293ee, v99
	v_exp_f32_e32 v85, v85
	v_fmamk_f32 v102, v87, 0x3e0293ee, v99
	v_fmamk_f32 v113, v96, 0x3e0293ee, v99
	v_fmamk_f32 v96, v77, 0x3e0293ee, v99
	v_exp_f32_e32 v77, v101
	v_exp_f32_e32 v100, v66
	v_add_f32_e32 v66, 0, v84
	v_fmamk_f32 v103, v88, 0x3e0293ee, v99
	v_exp_f32_e32 v83, v102
	v_add_f32_e32 v66, v86, v66
	v_fmamk_f32 v104, v89, 0x3e0293ee, v99
	v_fmamk_f32 v112, v95, 0x3e0293ee, v99
	v_fmamk_f32 v95, v76, 0x3e0293ee, v99
	v_exp_f32_e32 v76, v103
	v_add_f32_e32 v66, v82, v66
	v_fmamk_f32 v105, v90, 0x3e0293ee, v99
	v_fmamk_f32 v114, v97, 0x3e0293ee, v99
	v_fmamk_f32 v97, v78, 0x3e0293ee, v99
	v_exp_f32_e32 v78, v104
	v_add_f32_e32 v66, v85, v66
	v_fmamk_f32 v106, v91, 0x3e0293ee, v99
	v_fmamk_f32 v107, v92, 0x3e0293ee, v99
	v_fmamk_f32 v92, v73, 0x3e0293ee, v99
	v_exp_f32_e32 v73, v105
	v_add_f32_e32 v66, v77, v66
	v_fmamk_f32 v109, v94, 0x3e0293ee, v99
	v_fmamk_f32 v94, v75, 0x3e0293ee, v99
	v_exp_f32_e32 v75, v106
	v_add_f32_e32 v66, v83, v66
	v_fmamk_f32 v108, v93, 0x3e0293ee, v99
	v_fmamk_f32 v90, v71, 0x3e0293ee, v99
	v_exp_f32_e32 v71, v107
	v_add_f32_e32 v66, v76, v66
	v_fmamk_f32 v93, v74, 0x3e0293ee, v99
	v_exp_f32_e32 v74, v108
	v_add_f32_e32 v66, v78, v66
	v_fmamk_f32 v88, v69, 0x3e0293ee, v99
	v_exp_f32_e32 v69, v109
	v_add_f32_e32 v66, v73, v66
	v_fmamk_f32 v91, v72, 0x3e0293ee, v99
	v_exp_f32_e32 v72, v112
	v_add_f32_e32 v66, v75, v66
	v_fmamk_f32 v87, v68, 0x3e0293ee, v99
	v_exp_f32_e32 v68, v113
	v_add_f32_e32 v66, v71, v66
	v_fmamk_f32 v89, v70, 0x3e0293ee, v99
	v_exp_f32_e32 v70, v114
	v_add_f32_e32 v66, v74, v66
	v_fmamk_f32 v67, v67, 0x3e0293ee, v99
	v_add_f32_e32 v66, v69, v66
	v_exp_f32_e32 v101, v67
	v_add_f32_e32 v66, v72, v66
	v_exp_f32_e32 v87, v87
	v_add_f32_e32 v66, v68, v66
	v_exp_f32_e32 v88, v88
	v_add_f32_e32 v66, v70, v66
	v_exp_f32_e32 v89, v89
	v_add_f32_e32 v66, v100, v66
	v_exp_f32_e32 v90, v90
	v_add_f32_e32 v66, v101, v66
	v_exp_f32_e32 v91, v91
	v_add_f32_e32 v66, v87, v66
	v_exp_f32_e32 v92, v92
	v_add_f32_e32 v66, v88, v66
	v_exp_f32_e32 v93, v93
	v_add_f32_e32 v66, v89, v66
	v_exp_f32_e32 v94, v94
	v_add_f32_e32 v66, v90, v66
	v_exp_f32_e32 v95, v95
	v_add_f32_e32 v66, v91, v66
	v_exp_f32_e32 v96, v96
	v_add_f32_e32 v66, v92, v66
	v_fmamk_f32 v79, v79, 0x3e0293ee, v99
	v_exp_f32_e32 v97, v97
	v_add_f32_e32 v66, v93, v66
	v_fmamk_f32 v80, v80, 0x3e0293ee, v99
	v_exp_f32_e32 v102, v79
	v_add_f32_e32 v66, v94, v66
	v_fmac_f32_e32 v99, 0x3e0293ee, v81
	v_exp_f32_e32 v103, v80
	v_add_f32_e32 v66, v95, v66
	v_exp_f32_e32 v99, v99
	v_add_f32_e32 v66, v96, v66
	v_add_f32_e32 v66, v97, v66
	v_add_f32_e32 v66, v102, v66
	v_add_f32_e32 v66, v103, v66
	v_add_f32_e32 v66, v99, v66
	v_mov_b32_e32 v67, v66
	s_nop 1
	v_permlane32_swap_b32_e32 v66, v67
	v_cvt_pk_bf16_f32 v80, v84, v86
	v_cvt_pk_bf16_f32 v81, v82, v85
	v_cvt_pk_bf16_f32 v82, v77, v83
	v_cvt_pk_bf16_f32 v83, v76, v78
	v_cvt_pk_bf16_f32 v76, v73, v75
	v_cvt_pk_bf16_f32 v77, v71, v74
	v_cvt_pk_bf16_f32 v78, v69, v72
	v_cvt_pk_bf16_f32 v79, v68, v70
	v_cvt_pk_bf16_f32 v68, v100, v101
	v_cvt_pk_bf16_f32 v69, v87, v88
	v_cvt_pk_bf16_f32 v70, v89, v90
	v_cvt_pk_bf16_f32 v71, v91, v92
	v_cvt_pk_bf16_f32 v72, v93, v94
	v_cvt_pk_bf16_f32 v73, v95, v96
	v_cvt_pk_bf16_f32 v74, v97, v102
	v_cvt_pk_bf16_f32 v75, v103, v99
	s_nop 0
	v_permlane32_swap_b32_e32 v80, v82
	v_permlane32_swap_b32_e32 v81, v83
	v_permlane32_swap_b32_e32 v76, v78
	v_permlane32_swap_b32_e32 v77, v79
	v_permlane32_swap_b32_e32 v68, v70
	v_permlane32_swap_b32_e32 v69, v71
	v_permlane32_swap_b32_e32 v72, v74
	v_permlane32_swap_b32_e32 v73, v75
	ds_read_b64_tr_b16 v[84:85], v196 offset:0
	ds_read_b64_tr_b16 v[86:87], v196 offset:0x800
	ds_read_b64_tr_b16 v[88:89], v196 offset:0x1000
	ds_read_b64_tr_b16 v[90:91], v196 offset:0x1800
	ds_read_b64_tr_b16 v[92:93], v196 offset:0x2000
	ds_read_b64_tr_b16 v[94:95], v196 offset:0x2800
	ds_read_b64_tr_b16 v[100:101], v196 offset:0x3000
	ds_read_b64_tr_b16 v[102:103], v196 offset:0x3800
	s_waitcnt lgkmcnt(0)
	s_nop 0
	v_mfma_f32_32x32x16_bf16 v[2:17], v[80:83], v[84:87], v[2:17]
	ds_read_b64_tr_b16 v[84:85], v196 offset:0x200
	ds_read_b64_tr_b16 v[86:87], v196 offset:0xa00
	v_mfma_f32_32x32x16_bf16 v[2:17], v[76:79], v[88:91], v[2:17]
	ds_read_b64_tr_b16 v[88:89], v196 offset:0x1200
	ds_read_b64_tr_b16 v[90:91], v196 offset:0x1a00
	v_mfma_f32_32x32x16_bf16 v[2:17], v[68:71], v[92:95], v[2:17]
	ds_read_b64_tr_b16 v[92:93], v196 offset:0x2200
	ds_read_b64_tr_b16 v[94:95], v196 offset:0x2a00
	ds_read_b64_tr_b16 v[104:105], v196 offset:0x3200
	ds_read_b64_tr_b16 v[106:107], v196 offset:0x3a00
	v_mfma_f32_32x32x16_bf16 v[2:17], v[72:75], v[100:103], v[2:17]
	s_waitcnt lgkmcnt(0)
	v_mfma_f32_32x32x16_bf16 v[50:65], v[80:83], v[84:87], v[50:65]
	ds_read_b64_tr_b16 v[84:85], v196 offset:0x400
	ds_read_b64_tr_b16 v[86:87], v196 offset:0xc00
	v_mfma_f32_32x32x16_bf16 v[50:65], v[76:79], v[88:91], v[50:65]
	ds_read_b64_tr_b16 v[88:89], v196 offset:0x1400
	ds_read_b64_tr_b16 v[90:91], v196 offset:0x1c00
	v_mfma_f32_32x32x16_bf16 v[50:65], v[68:71], v[92:95], v[50:65]
	ds_read_b64_tr_b16 v[92:93], v196 offset:0x2400
	ds_read_b64_tr_b16 v[94:95], v196 offset:0x2c00
	ds_read_b64_tr_b16 v[100:101], v196 offset:0x3400
	ds_read_b64_tr_b16 v[102:103], v196 offset:0x3c00
	v_mfma_f32_32x32x16_bf16 v[50:65], v[72:75], v[104:107], v[50:65]
	s_waitcnt lgkmcnt(0)
	v_mfma_f32_32x32x16_bf16 v[34:49], v[80:83], v[84:87], v[34:49]
	ds_read_b64_tr_b16 v[84:85], v196 offset:0x600
	ds_read_b64_tr_b16 v[86:87], v196 offset:0xe00
	v_mfma_f32_32x32x16_bf16 v[34:49], v[76:79], v[88:91], v[34:49]
	ds_read_b64_tr_b16 v[88:89], v196 offset:0x1600
	ds_read_b64_tr_b16 v[90:91], v196 offset:0x1e00
	v_mfma_f32_32x32x16_bf16 v[34:49], v[68:71], v[92:95], v[34:49]
	ds_read_b64_tr_b16 v[92:93], v196 offset:0x2600
	ds_read_b64_tr_b16 v[94:95], v196 offset:0x2e00
	ds_read_b64_tr_b16 v[104:105], v196 offset:0x3600
	ds_read_b64_tr_b16 v[106:107], v196 offset:0x3e00
	v_mfma_f32_32x32x16_bf16 v[34:49], v[72:75], v[100:103], v[34:49]
	s_waitcnt lgkmcnt(0)
	v_mfma_f32_32x32x16_bf16 v[18:33], v[80:83], v[84:87], v[18:33]
	v_mfma_f32_32x32x16_bf16 v[18:33], v[76:79], v[88:91], v[18:33]
	v_mfma_f32_32x32x16_bf16 v[18:33], v[68:71], v[92:95], v[18:33]
	v_mfma_f32_32x32x16_bf16 v[18:33], v[72:75], v[104:107], v[18:33]
	s_and_saveexec_b64 s[6:7], s[4:5]
	s_cbranch_execz .LBB0_507
	v_add_f32_e32 v68, v110, v111
	v_fmac_f32_e32 v68, v223, v162
	v_add_f32_e32 v66, v66, v67
	v_fmac_f32_e32 v66, v68, v98
	ds_write_b32 v222, v66
	s_branch .LBB0_507
